# S35: S34 + attention unit prologue: redundant compiler vmcnt(0) before the first QK MFMA reduced to lgkmcnt(0) (Q already covered by the earlier counted vmcnt(4); third K/V DMA group no longer drained
# baseline (speedup 1.0000x reference)
; __device__ __forceinline__ int v_rd_base(int lane) { return ((lane & 3) << 3) | (((lane >> 2) & 3) << 6) | (((lane >> 4) & 1) << 5) | (((lane >> 5) & 1) << 8); }
; #define TILE_BAR(n) do { asm volatile("s_waitcnt vmcnt(" #n ")" ::: "memory"); __builtin_amdgcn_s_barrier(); asm volatile("" ::: "memory"); } while (0)
; __device__ __forceinline__ void attn_unit(const bf16* __restrict__ Qb, const bf16* __restrict__ Kh, const bf16* __restrict__ Vh, int klat0, int nlt, int kctx0, int NT,
;                                           float lam, float post, const float* __restrict__ subw, bf16* __restrict__ Ob, char* lds) {
;     ...
;   const int tid = tid_l, wid = __builtin_amdgcn_readfirstlane(tid >> 6), lane = tid & 63, r32 = lane & 31, hi = lane >> 5;
;   const int sbr = wid >> 2, wq = wid & 3, sb = sbr * 128;
;   char* K_lds = lds + LDS_KR; char* V_lds = lds + LDS_VR;
;   float* ws = (float*)(lds + LDS_WS) + wid * 64; float* li_l = ws; float* al_l = ws + 32;
;   float m_reg = -1e30f, l_reg = 0; f32x16 o[4] = {}; bf16x8 qr[4];
;   const bf16* Qw = Qb + (long)(wq * 32 + r32) * LDK + sbr * 64 + hi * 8;
; #pragma unroll
;   for (int d0 = 0; d0 < 4; ++d0) qr[d0] = *reinterpret_cast<const bf16x8*>(Qw + d0 * 16);
;   unsigned koff[2], voff[2];
; #pragma unroll
;   for (int q = 0; q < 2; ++q) { const int ch = (q * 8 + wid) * 64 + lane;
;     { const int row = ch >> 4, cpos = ch & 15, csrc = cpos ^ (row & 7); koff[q] = (unsigned)(row * LDK + csrc * 8) * 2u; }
;     { const int pb = ch * 16, sub = pb >> 9, within = (pb & 511) >> 1, kk = (sub >> 2) * 8 + (within >> 5), c = (sub & 3) * 32 + (within & 31);
;       const int k = (kk & ~0xC) | ((kk & 4) << 1) | ((kk & 8) >> 1); voff[q] = (unsigned)(k * LDK + c) * 2u; } }
;   const int vb0 = (int)(uintptr_t)V_lds + v_rd_base(lane);
;   const unsigned ldsw = (unsigned)wid * 1024u;
;   typedef __attribute__((address_space(3))) unsigned lds_u32;
;     ...
;   f32x16 pA0, pA1, pB0, pB1; float mnA, mnB, alA, alB; bf16x8 pa0, pa1, pa2, pa3;
;   DMA_TILE(0); DMA_TILE(1); TILE_BAR(4);
;   DMA_TILE(2);
;   qkt(pA0, pA1, KS(0), qr, r32, hi, sb); partialSM(pA0, pA1, m_reg, mnA, alA);
.LBB0_748:
	s_and_b64 vcc, exec, s[0:1]
	s_cbranch_vccz .LBB0_715
	s_ashr_i32 s0, s8, 9
	s_ashr_i32 s1, s0, 31
	s_lshl_b64 s[4:5], s[0:1], 13
	s_lshl_b32 s1, s8, 7
	s_and_b32 s1, s1, 0x1f80
	s_or_b32 s4, s4, s1
	s_lshl_b64 s[6:7], s[4:5], 11
	v_readlane_b32 s1, v249, 48
	s_add_u32 s1, s1, s6
	v_readlane_b32 s6, v249, 49
	s_addc_u32 s7, s6, s7
	s_lshl_b32 s6, s8, 1
	s_and_b32 s6, s6, 0x380
	s_lshl_b32 s16, s6, 1
	s_add_u32 s6, s1, s16
	s_addc_u32 s7, s7, 0
	v_readlane_b32 s1, v251, 17
	s_add_u32 s20, s1, s16
	v_readlane_b32 s1, v251, 18
	s_addc_u32 s21, s1, 0
	v_readlane_b32 s1, v251, 19
	s_add_u32 s22, s1, s16
	v_readlane_b32 s1, v251, 20
	v_mov_b32_e32 v4, v0
	s_addc_u32 s23, s1, 0
	s_lshl_b32 s8, s0, 13
	s_lshl_b32 s26, s0, 8
	v_mov_b32_e32 v141, v147
	v_readfirstlane_b32 s0, v4
	s_ashr_i32 s1, s0, 6
	v_and_b32_e32 v138, 31, v4
	s_and_b32 s19, s1, 3
	v_lshlrev_b32_e32 v2, 11, v138
	s_ashr_i32 s17, s0, 8
	v_lshl_or_b32 v146, s19, 16, v2
	v_lshl_add_u64 v[2:3], s[6:7], 0, v[146:147]
	s_lshl_b32 s6, s17, 6
	s_ashr_i32 s7, s6, 31
	v_bfe_u32 v5, v4, 2, 2
	v_lshrrev_b32_e32 v7, 1, v4
	v_bfe_u32 v139, v4, 5, 1
	s_and_b32 s9, s0, 0xffffffc0
	v_lshl_add_u64 v[2:3], s[6:7], 1, v[2:3]
	v_and_or_b32 v5, v7, 8, v5
	v_mov_b32_e32 v7, s0
	s_movk_i32 s6, 0xffc0
	v_lshlrev_b32_e32 v140, 4, v139
	v_bfi_b32 v7, s6, v7, v4
	s_ashr_i32 s6, s9, 4
	v_and_b32_e32 v58, 63, v4
	v_lshl_add_u64 v[2:3], v[2:3], 0, v[140:141]
	s_and_b32 s7, s6, 0x1ffff0
	s_lshr_b32 s6, s6, 1
	s_lshl_b32 s10, s9, 2
	global_load_dwordx4 v[126:129], v[2:3], off
	global_load_dwordx4 v[122:125], v[2:3], off offset:32
	global_load_dwordx4 v[118:121], v[2:3], off offset:64
	global_load_dwordx4 v[114:117], v[2:3], off offset:96
	v_and_b32_e32 v2, 15, v4
	v_lshlrev_b32_e32 v3, 3, v58
	v_ashrrev_i32_e32 v8, 4, v7
	s_and_b32 s6, s6, 4
	s_add_i32 s18, s10, 0
	v_and_b32_e32 v6, 24, v3
	v_bitop3_b32 v9, v8, v2, 15 bitop3:0x6c
	v_lshlrev_b32_e32 v8, 11, v8
	s_movk_i32 s10, 0x60
	s_or_b32 s6, s7, s6
	s_addk_i32 s9, 0x200
	v_lshl_or_b32 v146, v9, 4, v8
	v_and_or_b32 v7, v7, s10, v6
	v_or_b32_e32 v8, s6, v5
	s_ashr_i32 s6, s9, 4
	v_lshlrev_b32_e32 v7, 1, v7
	s_and_b32 s7, s6, 0x1ffff0
	s_lshr_b32 s6, s6, 1
	v_lshl_or_b32 v142, v8, 11, v7
	v_or_b32_e32 v7, s9, v58
	s_and_b32 s6, s6, 4
	v_ashrrev_i32_e32 v8, 4, v7
	s_or_b32 s6, s7, s6
	s_ashr_i32 s9, s8, 31
	s_addk_i32 s26, 0x4000
	s_add_i32 s18, s18, 0x1c000
	v_bitop3_b32 v2, v8, v2, 15 bitop3:0x6c
	v_lshlrev_b32_e32 v8, 11, v8
	v_or_b32_e32 v5, s6, v5
	s_lshl_b32 s31, s1, 10
	s_lshl_b64 s[6:7], s[8:9], 11
	v_lshl_or_b32 v144, v2, 4, v8
	v_and_or_b32 v2, v7, s10, v6
	s_add_u32 s10, s20, s6
	s_addc_u32 s11, s21, s7
	s_add_u32 s6, s22, s6
	s_addc_u32 s7, s23, s7
	s_cmp_lg_u32 0, -1
	s_cselect_b32 s1, 0, 0
	s_add_i32 s27, s31, s1
	s_add_i32 s1, s1, 0xc000
	s_add_i32 s36, s31, s1
	s_mov_b32 m0, s27
	v_lshlrev_b32_e32 v2, 1, v2
	global_load_lds_dwordx4 v146, s[10:11]
	s_mov_b32 m0, s36
	v_lshl_or_b32 v154, v5, 11, v2
	global_load_lds_dwordx4 v142, s[6:7]
	s_add_i32 m0, s27, 0x2000
	v_lshlrev_b32_e32 v2, 1, v4
	global_load_lds_dwordx4 v144, s[10:11]
	s_add_i32 m0, s27, 0xe000
	v_and_b32_e32 v2, 32, v2
	global_load_lds_dwordx4 v154, s[6:7]
	s_or_b32 s6, s8, 64
	s_ashr_i32 s7, s6, 31
	s_lshl_b64 s[6:7], s[6:7], 11
	v_lshlrev_b32_e32 v4, 4, v4
	s_add_u32 s10, s20, s6
	v_and_or_b32 v2, v4, s72, v2
	v_and_b32_e32 v3, 0x100, v3
	s_addc_u32 s11, s21, s7
	v_or3_b32 v141, v2, v3, v6
	s_add_u32 s6, s22, s6
	v_add_u32_e32 v164, s1, v141
	s_addc_u32 s7, s23, s7
	s_add_i32 m0, s27, 0x4000
	s_add_i32 s1, s27, 0x10000
	global_load_lds_dwordx4 v146, s[10:11]
	s_mov_b32 m0, s1
	v_lshl_or_b32 v10, s17, 7, v140
	global_load_lds_dwordx4 v142, s[6:7]
	s_add_i32 m0, s27, 0x6000
	v_lshlrev_b32_e32 v11, 8, v138
	global_load_lds_dwordx4 v144, s[10:11]
	s_add_i32 m0, s27, 0x12000
	v_and_b32_e32 v12, 0xf0, v4
	global_load_lds_dwordx4 v154, s[6:7]
	s_or_b32 s6, s8, 0x80
	s_ashr_i32 s7, s6, 31
	s_lshl_b64 s[6:7], s[6:7], 11
	s_add_u32 s10, s20, s6
	s_addc_u32 s11, s21, s7
	s_add_u32 s6, s22, s6
	s_waitcnt vmcnt(4)
	s_barrier
	s_addc_u32 s7, s23, s7
	s_add_i32 m0, s27, 0x8000
	s_add_i32 s1, s27, 0x14000
	global_load_lds_dwordx4 v146, s[10:11]
	s_mov_b32 m0, s1
	v_or_b32_e32 v13, 32, v10
	global_load_lds_dwordx4 v142, s[6:7]
	s_add_i32 m0, s27, 0xa000
	v_xad_u32 v169, v10, v12, v11
	global_load_lds_dwordx4 v144, s[10:11]
	s_add_i32 m0, s27, 0x16000
	v_xad_u32 v170, v13, v12, v11
	global_load_lds_dwordx4 v154, s[6:7]
	v_or_b32_e32 v13, 64, v10
	v_or_b32_e32 v10, 0x60, v10
	v_xad_u32 v171, v13, v12, v11
	v_xad_u32 v172, v10, v12, v11
	v_add_u32_e32 v165, 0, v169
	v_add_u32_e32 v166, 0, v170
	v_add_u32_e32 v167, 0, v171
	v_add_u32_e32 v168, 0, v172
	ds_read_b128 v[2:5], v165
	ds_read_b128 v[6:9], v165 offset:8192
	ds_read_b128 v[34:37], v166
	ds_read_b128 v[38:41], v166 offset:8192
	ds_read_b128 v[42:45], v167
	ds_read_b128 v[46:49], v167 offset:8192
	ds_read_b128 v[50:53], v168
	ds_read_b128 v[54:57], v168 offset:8192
	v_mov_b32_e32 v143, v147
	v_mov_b32_e32 v145, v147
	v_mov_b32_e32 v155, v147
	s_waitcnt lgkmcnt(0)
	s_waitcnt lgkmcnt(0)
	v_mfma_f32_32x32x16_bf16 v[18:33], v[2:5], v[126:129], 0
	s_mov_b32 s6, 0x3e38aa3b
	s_waitcnt vmcnt(4)
	s_barrier
; #define SBAR() __builtin_amdgcn_sched_barrier(0)
; __device__ __forceinline__ void partialSM(f32x16& p0, f32x16& p1, float& m_reg, float& mn, float& alpha) {
;   constexpr float C = SCALE * 1.4426950408889634f;
;   float pmax = p0[0]; for (int r = 1; r < 16; ++r) pmax = fmaxf(pmax, p0[r]); for (int r = 0; r < 16; ++r) pmax = fmaxf(pmax, p1[r]);
;   { auto rr = __builtin_amdgcn_permlane32_swap(__float_as_uint(pmax), __float_as_uint(pmax), false, false);
;     pmax = fmaxf(__uint_as_float(rr[0]), __uint_as_float(rr[1])); }
;   if (__builtin_expect(__all(pmax - m_reg <= THR / SCALE), 1)) { mn = m_reg; alpha = 1.f; }
;   else { mn = fmaxf(m_reg, pmax); alpha = __builtin_amdgcn_exp2f((m_reg - mn) * C); m_reg = mn; }
;   float mnC = -mn * C;
;   for (int r = 0; r < 16; ++r) p0[r] = fmaf(p0[r], C, mnC); for (int r = 0; r < 16; ++r) p1[r] = fmaf(p1[r], C, mnC);
;   for (int r = 0; r < 16; ++r) p0[r] = __builtin_amdgcn_exp2f(p0[r]);
; }
; __device__ __forceinline__ void kmma(f32x16& p0, f32x16& p1, const bf16x8 (&kf)[8], const bf16x8* qr) {
;   asm volatile("s_waitcnt lgkmcnt(0)" ::: "memory"); SBAR();
;   p0 = f32x16{}; p1 = f32x16{};
; #pragma unroll
;   for (int d0 = 0; d0 < 4; ++d0) { p0 = __builtin_amdgcn_mfma_f32_32x32x16_bf16(kf[2 * d0], qr[d0], p0, 0, 0, 0); p1 = __builtin_amdgcn_mfma_f32_32x32x16_bf16(kf[2 * d0 + 1], qr[d0], p1, 0, 0, 0); }
; }
	v_cmp_gt_u32_e64 s[40:41], 32, v58
	v_lshl_add_u32 v162, v138, 2, s18
	v_mfma_f32_32x32x16_bf16 v[18:33], v[34:37], v[122:125], v[18:33]
	v_mfma_f32_32x32x16_bf16 v[2:17], v[6:9], v[126:129], 0
	v_mfma_f32_32x32x16_bf16 v[18:33], v[42:45], v[118:121], v[18:33]
	v_mfma_f32_32x32x16_bf16 v[2:17], v[38:41], v[122:125], v[2:17]
	v_mfma_f32_32x32x16_bf16 v[18:33], v[50:53], v[114:117], v[18:33]
	v_mfma_f32_32x32x16_bf16 v[2:17], v[46:49], v[118:121], v[2:17]
	s_nop 10
	v_max_f32_e32 v34, v19, v19
	v_max_f32_e32 v35, v18, v18
	v_max_f32_e32 v34, v35, v34
	v_max3_f32 v34, v34, v20, v21
	v_max3_f32 v34, v34, v22, v23
	v_max3_f32 v34, v34, v24, v25
	v_max3_f32 v34, v34, v26, v27
	v_mfma_f32_32x32x16_bf16 v[2:17], v[54:57], v[114:117], v[2:17]
	v_max3_f32 v34, v34, v28, v29
	v_max3_f32 v34, v34, v30, v31
	v_max3_f32 v34, v34, v32, v33
	s_nop 8
	v_max3_f32 v34, v34, v2, v3
	v_max3_f32 v34, v34, v4, v5
	v_max3_f32 v34, v34, v6, v7
	v_max3_f32 v34, v34, v8, v9
	v_max3_f32 v34, v34, v10, v11
	v_max3_f32 v34, v34, v12, v13
	v_max3_f32 v34, v34, v14, v15
	v_max3_f32 v34, v34, v16, v17
	v_mov_b32_e32 v35, v34
	s_nop 1
	v_permlane32_swap_b32_e32 v34, v35
	v_max_f32_e32 v35, v35, v35
	v_max_f32_e32 v34, v34, v34
	v_max_f32_e32 v34, v34, v35
	v_add_f32_e32 v35, 0x7149f2ca, v34
	v_max_f32_e32 v34, 0xf149f2ca, v34
	v_cmp_ge_f32_e32 vcc, s63, v35
	v_sub_f32_e32 v35, 0xf149f2ca, v34
	v_mul_f32_e32 v35, 0x3e38aa3b, v35
	v_exp_f32_e32 v35, v35
	s_cmp_eq_u64 vcc, exec
	s_cselect_b64 vcc, -1, 0
	v_cndmask_b32_e32 v174, v34, v248, vcc
	v_mul_f32_e32 v34, 0xbe38aa3b, v174
	v_cndmask_b32_e64 v173, v35, 1.0, vcc
	v_mov_b32_e32 v35, v34
	v_fmamk_f32 v18, v18, 0x3e38aa3b, v34
	v_fmamk_f32 v19, v19, 0x3e38aa3b, v34
	v_fmamk_f32 v20, v20, 0x3e38aa3b, v34
	v_fmamk_f32 v21, v21, 0x3e38aa3b, v34
	v_fmamk_f32 v22, v22, 0x3e38aa3b, v34
	v_fmamk_f32 v23, v23, 0x3e38aa3b, v34
	v_fmamk_f32 v24, v24, 0x3e38aa3b, v34
	v_fmamk_f32 v25, v25, 0x3e38aa3b, v34
	v_fmamk_f32 v26, v26, 0x3e38aa3b, v34
	v_fmamk_f32 v27, v27, 0x3e38aa3b, v34
	v_fmamk_f32 v28, v28, 0x3e38aa3b, v34
	v_fmamk_f32 v29, v29, 0x3e38aa3b, v34
	v_fmamk_f32 v30, v30, 0x3e38aa3b, v34
	v_fmamk_f32 v31, v31, 0x3e38aa3b, v34
	v_fmamk_f32 v32, v32, 0x3e38aa3b, v34
	v_fmac_f32_e32 v35, 0x3e38aa3b, v33
	v_exp_f32_e32 v175, v18
	v_exp_f32_e32 v177, v19
	v_exp_f32_e32 v192, v20
	v_exp_f32_e32 v195, v21
	v_exp_f32_e32 v196, v22
	v_exp_f32_e32 v199, v23
	v_exp_f32_e32 v200, v24
	v_exp_f32_e32 v203, v25
	v_exp_f32_e32 v176, v26
	v_exp_f32_e32 v193, v27
	v_exp_f32_e32 v194, v28
	v_exp_f32_e32 v197, v29
	v_exp_f32_e32 v198, v30
	v_exp_f32_e32 v201, v31
	v_exp_f32_e32 v202, v32
	v_exp_f32_e32 v204, v35
	s_cmpk_lt_u32 s0, 0x100
	v_pk_fma_f32 v[80:81], v[16:17], s[6:7], v[34:35] op_sel_hi:[1,0,0]
	v_pk_fma_f32 v[78:79], v[14:15], s[6:7], v[34:35] op_sel_hi:[1,0,0]
	v_pk_fma_f32 v[76:77], v[12:13], s[6:7], v[34:35] op_sel_hi:[1,0,0]
	v_pk_fma_f32 v[74:75], v[10:11], s[6:7], v[34:35] op_sel_hi:[1,0,0]
	v_pk_fma_f32 v[72:73], v[8:9], s[6:7], v[34:35] op_sel_hi:[1,0,0]
	v_pk_fma_f32 v[70:71], v[6:7], s[6:7], v[34:35] op_sel_hi:[1,0,0]
	v_pk_fma_f32 v[68:69], v[4:5], s[6:7], v[34:35] op_sel_hi:[1,0,0]
	v_pk_fma_f32 v[66:67], v[2:3], s[6:7], v[34:35] op_sel_hi:[1,0,0]
	s_cselect_b64 s[6:7], -1, 0
	s_ashr_i32 s30, s26, 31
	s_cmpk_gt_u32 s0, 0xff
	s_mov_b64 s[0:1], -1
	s_branch .LBB0_768
	.p2align 8
	v_mov_b32_e32 v18, v147
	v_mov_b32_e32 v19, v147
	v_mov_b32_e32 v32, v147
	v_mov_b32_e32 v33, v147
	v_mov_b32_e32 v20, v147
	v_mov_b32_e32 v21, v147
	v_mov_b32_e32 v22, v147
	v_mov_b32_e32 v23, v147
	v_mov_b32_e32 v24, v147
	v_mov_b32_e32 v25, v147
	v_mov_b32_e32 v26, v147
	v_mov_b32_e32 v27, v147
	v_mov_b32_e32 v28, v147
	v_mov_b32_e32 v29, v147
	v_mov_b32_e32 v30, v147
	v_mov_b32_e32 v31, v147
	v_mov_b64_e32 v[64:65], v[32:33]
	v_mov_b64_e32 v[48:49], v[32:33]
	v_mov_b64_e32 v[2:3], v[18:19]
	v_mov_b64_e32 v[106:107], v[80:81]
	v_mov_b32_e32 v163, 0
	s_mov_b32 s12, 1
	s_mov_b32 s37, 0x10000
	v_mov_b64_e32 v[62:63], v[30:31]
	v_mov_b64_e32 v[60:61], v[28:29]
	v_mov_b64_e32 v[58:59], v[26:27]
	v_mov_b64_e32 v[56:57], v[24:25]
	v_mov_b64_e32 v[54:55], v[22:23]
	v_mov_b64_e32 v[52:53], v[20:21]
	v_mov_b64_e32 v[50:51], v[18:19]
	v_mov_b64_e32 v[46:47], v[30:31]
	v_mov_b64_e32 v[44:45], v[28:29]
	v_mov_b64_e32 v[42:43], v[26:27]
	v_mov_b64_e32 v[40:41], v[24:25]
	v_mov_b64_e32 v[38:39], v[22:23]
	v_mov_b64_e32 v[36:37], v[20:21]
	v_mov_b64_e32 v[34:35], v[18:19]
	v_mov_b64_e32 v[4:5], v[20:21]
	v_mov_b64_e32 v[6:7], v[22:23]
	v_mov_b64_e32 v[8:9], v[24:25]
	v_mov_b64_e32 v[10:11], v[26:27]
	v_mov_b64_e32 v[12:13], v[28:29]
	v_mov_b64_e32 v[14:15], v[30:31]
	v_mov_b64_e32 v[16:17], v[32:33]
	v_mov_b32_e32 v207, v173
	v_mov_b64_e32 v[104:105], v[78:79]
	v_mov_b64_e32 v[102:103], v[76:77]
	v_mov_b64_e32 v[100:101], v[74:75]
	v_mov_b64_e32 v[98:99], v[72:73]
	v_mov_b64_e32 v[96:97], v[70:71]
	v_mov_b64_e32 v[94:95], v[68:69]
	v_mov_b64_e32 v[92:93], v[66:67]
	v_mov_b32_e32 v206, v174
	v_mov_b32_e32 v214, v175
	v_mov_b32_e32 v215, v177
	v_mov_b32_e32 v131, v192
	v_mov_b32_e32 v213, v195
	v_mov_b32_e32 v132, v196
	v_mov_b32_e32 v137, v199
	v_mov_b32_e32 v133, v200
	v_mov_b32_e32 v136, v203
	v_mov_b32_e32 v134, v176
	v_mov_b32_e32 v135, v193
	v_mov_b32_e32 v112, v194
	v_mov_b32_e32 v113, v197
	v_mov_b32_e32 v110, v198
	v_mov_b32_e32 v111, v201
	v_mov_b32_e32 v108, v202
	v_mov_b32_e32 v109, v204
